# v56: v55 + running-max-as-MFMA-C-operand also in the .LBB0_381 attention units
# speedup vs baseline: 1.0203x; 1.0045x over previous
; #define LAS __attribute__((address_space(3)))
; template <int DK, bool IS_A>
; __device__ __forceinline__ void attn_unit(const Params& P, int l, LAS unsigned char* lds, int b, int grp, int qtok0, int nkeys) {
;     ...
;             __builtin_amdgcn_s_setprio(1);
; #pragma unroll
;             for (int i = 0; i < DK / 16; ++i)
; #pragma unroll
;                 for (int jj = 0; jj < 2; ++jj) {
;                     const bf16x8 kf = *(const LAS bf16x8*)(kb + jj * 32 * AK_PITCH + i * 32);
;                     pa[jj] = __builtin_amdgcn_mfma_f32_32x32x16_bf16(kf, qa[i], pa[jj], 0, 0, 0);
;                     pb[jj] = __builtin_amdgcn_mfma_f32_32x32x16_bf16(kf, qb[i], pb[jj], 0, 0, 0);
;                 }
;             __builtin_amdgcn_s_setprio(0);
;     ...
;             AT_SOFTMAX(pa, ma, la, oa0, oa1);
;             AT_SOFTMAX(pb, mb, lb_, ob0, ob1);
.LBB0_386:
	s_bitcmp1_b32 s12, 0
	s_cselect_b32 s10, 0x8a00, 0
	s_add_i32 s10, s10, 0
	v_add_u32_e32 v64, s10, v176
	v_add_u32_e32 v186, v64, v178
	s_setprio 1
	ds_read_b128 v[64:67], v186
	ds_read_b128 v[188:191], v186 offset:32
	s_waitcnt lgkmcnt(1)
	v_mfma_f32_32x32x16_bf16 v[112:127], v[64:67], v[142:145], v[236:251]
	v_mfma_f32_32x32x16_bf16 v[96:111], v[64:67], v[158:161], 0
	ds_read_b128 v[64:67], v186 offset:4608
	s_waitcnt lgkmcnt(1)
	v_mfma_f32_32x32x16_bf16 v[112:127], v[188:191], v[150:153], v[112:127]
	v_mfma_f32_32x32x16_bf16 v[96:111], v[188:191], v[154:157], v[96:111]
	ds_read_b128 v[188:191], v186 offset:4640
	s_waitcnt lgkmcnt(1)
	v_mfma_f32_32x32x16_bf16 v[80:95], v[64:67], v[142:145], v[236:251]
	v_mfma_f32_32x32x16_bf16 v[64:79], v[64:67], v[158:161], 0
	s_waitcnt lgkmcnt(0)
	v_mfma_f32_32x32x16_bf16 v[80:95], v[188:191], v[150:153], v[80:95]
	v_mfma_f32_32x32x16_bf16 v[64:79], v[188:191], v[154:157], v[64:79]
	s_setprio 0
	s_nop 9
	v_max_f32_e32 v180, v112, v80
	v_max3_f32 v181, v81, v114, v82
	v_max3_f32 v180, v180, v113, v115
	v_max3_f32 v181, v181, v116, v84
	v_max3_f32 v180, v180, v83, v117
	v_max3_f32 v181, v181, v118, v86
	v_max3_f32 v180, v180, v85, v119
	v_max3_f32 v181, v181, v120, v88
	v_max3_f32 v180, v180, v87, v121
	v_max3_f32 v181, v181, v122, v90
	v_max3_f32 v180, v180, v89, v123
	v_max3_f32 v181, v181, v124, v92
	v_max3_f32 v180, v180, v91, v125
	v_max3_f32 v181, v181, v126, v94
	v_max3_f32 v180, v180, v93, v127
	v_max3_f32 v180, v180, v95, v181
	v_sub_f32_e32 v180, v180, v236
	ds_bpermute_b32 v181, v163, v180
	s_waitcnt lgkmcnt(0)
	v_max3_f32 v187, v182, v180, v181
	v_add_f32_e32 v181, 0x41000000, v182
	v_cmp_gt_f32_e32 vcc, v187, v181
	s_cbranch_vccz .LBB0_388
	v_add_f32_e32 v181, v187, v236
	v_sub_f32_e32 v112, v112, v181
	v_sub_f32_e32 v113, v113, v181
	v_sub_f32_e32 v114, v114, v181
	v_sub_f32_e32 v115, v115, v181
	v_sub_f32_e32 v116, v116, v181
	v_sub_f32_e32 v117, v117, v181
	v_sub_f32_e32 v118, v118, v181
	v_sub_f32_e32 v119, v119, v181
	v_sub_f32_e32 v120, v120, v181
	v_sub_f32_e32 v121, v121, v181
	v_sub_f32_e32 v122, v122, v181
	v_sub_f32_e32 v123, v123, v181
	v_sub_f32_e32 v124, v124, v181
	v_sub_f32_e32 v125, v125, v181
	v_sub_f32_e32 v126, v126, v181
	v_sub_f32_e32 v127, v127, v181
	v_sub_f32_e32 v80, v80, v181
	v_sub_f32_e32 v81, v81, v181
	v_sub_f32_e32 v82, v82, v181
	v_sub_f32_e32 v83, v83, v181
	v_sub_f32_e32 v84, v84, v181
	v_sub_f32_e32 v85, v85, v181
	v_sub_f32_e32 v86, v86, v181
	v_sub_f32_e32 v87, v87, v181
	v_sub_f32_e32 v88, v88, v181
	v_sub_f32_e32 v89, v89, v181
	v_sub_f32_e32 v90, v90, v181
	v_sub_f32_e32 v91, v91, v181
	v_sub_f32_e32 v92, v92, v181
	v_sub_f32_e32 v93, v93, v181
	v_sub_f32_e32 v94, v94, v181
	v_sub_f32_e32 v95, v95, v181
	v_sub_f32_e32 v236, 0, v187
	v_sub_f32_e32 v237, 0, v187
	v_sub_f32_e32 v238, 0, v187
	v_sub_f32_e32 v239, 0, v187
	v_sub_f32_e32 v240, 0, v187
	v_sub_f32_e32 v241, 0, v187
	v_sub_f32_e32 v242, 0, v187
	v_sub_f32_e32 v243, 0, v187
	v_sub_f32_e32 v244, 0, v187
	v_sub_f32_e32 v245, 0, v187
	v_sub_f32_e32 v246, 0, v187
	v_sub_f32_e32 v247, 0, v187
	v_sub_f32_e32 v248, 0, v187
	v_sub_f32_e32 v249, 0, v187
	v_sub_f32_e32 v250, 0, v187
	v_sub_f32_e32 v251, 0, v187
	v_sub_f32_e32 v180, v182, v187
	v_exp_f32_e32 v180, v180
	s_nop 0
	v_pk_mul_f32 v[62:63], v[62:63], v[180:181] op_sel_hi:[1,0]
	v_pk_mul_f32 v[60:61], v[60:61], v[180:181] op_sel_hi:[1,0]
	v_pk_mul_f32 v[58:59], v[58:59], v[180:181] op_sel_hi:[1,0]
	v_pk_mul_f32 v[56:57], v[56:57], v[180:181] op_sel_hi:[1,0]
	v_pk_mul_f32 v[54:55], v[54:55], v[180:181] op_sel_hi:[1,0]
	v_pk_mul_f32 v[52:53], v[52:53], v[180:181] op_sel_hi:[1,0]
	v_pk_mul_f32 v[50:51], v[50:51], v[180:181] op_sel_hi:[1,0]
	v_pk_mul_f32 v[48:49], v[48:49], v[180:181] op_sel_hi:[1,0]
	v_pk_mul_f32 v[46:47], v[46:47], v[180:181] op_sel_hi:[1,0]
	v_pk_mul_f32 v[44:45], v[44:45], v[180:181] op_sel_hi:[1,0]
	v_pk_mul_f32 v[42:43], v[42:43], v[180:181] op_sel_hi:[1,0]
	v_pk_mul_f32 v[40:41], v[40:41], v[180:181] op_sel_hi:[1,0]
	v_pk_mul_f32 v[38:39], v[38:39], v[180:181] op_sel_hi:[1,0]
	v_pk_mul_f32 v[36:37], v[36:37], v[180:181] op_sel_hi:[1,0]
	v_pk_mul_f32 v[34:35], v[34:35], v[180:181] op_sel_hi:[1,0]
	v_pk_mul_f32 v[32:33], v[32:33], v[180:181] op_sel_hi:[1,0]
	v_mul_f32_e32 v184, v184, v180
	s_branch .LBB0_389

; #define LAS __attribute__((address_space(3)))
; __device__ __forceinline__ unsigned pk2(float lo, float hi) { f32x2_t v = {lo, hi}; bf16x2_t b = __builtin_convertvector(v, bf16x2_t); return __builtin_bit_cast(unsigned, b); }
; template <int DK, bool IS_A>
; __device__ __forceinline__ void attn_unit(const Params& P, int l, LAS unsigned char* lds, int b, int grp, int qtok0, int nkeys) {
;     ...
;             AT_SOFTMAX(pa, ma, la, oa0, oa1);
;             AT_SOFTMAX(pb, mb, lb_, ob0, ob1);
;     ...
; #pragma unroll
;             for (int ks = 0; ks < 4; ++ks) {
;                 const int o8 = 8 * (ks & 1);
;                 u32x4 w; const f32x16& xa = pa[ks >> 1]; const f32x16& xb = pb[ks >> 1];
;                 w.x = pk2(xa[o8], xa[o8 + 1]); w.y = pk2(xa[o8 + 2], xa[o8 + 3]); w.z = pk2(xa[o8 + 4], xa[o8 + 5]); w.w = pk2(xa[o8 + 6], xa[o8 + 7]);
;                 const bf16x8 pfa = __builtin_bit_cast(bf16x8, w);
;                 w.x = pk2(xb[o8], xb[o8 + 1]); w.y = pk2(xb[o8 + 2], xb[o8 + 3]); w.z = pk2(xb[o8 + 4], xb[o8 + 5]); w.w = pk2(xb[o8 + 6], xb[o8 + 7]);
;                 const bf16x8 pfb = __builtin_bit_cast(bf16x8, w);
;                 const u32x2 a0 = *(const LAS u32x2*)(vb + ks * 32), a1 = *(const LAS u32x2*)(vb + ks * 32 + 16);
;                 const u32x2 c0 = *(const LAS u32x2*)(vb + 32 * AV_PITCH + ks * 32), c1 = *(const LAS u32x2*)(vb + 32 * AV_PITCH + ks * 32 + 16);
;                 const bf16x8 v0 = __builtin_bit_cast(bf16x8, ((u32x4){a0.x, a0.y, a1.x, a1.y})), v1 = __builtin_bit_cast(bf16x8, ((u32x4){c0.x, c0.y, c1.x, c1.y}));
;                 oa0 = __builtin_amdgcn_mfma_f32_32x32x16_bf16(v0, pfa, oa0, 0, 0, 0);
;                 oa1 = __builtin_amdgcn_mfma_f32_32x32x16_bf16(v1, pfa, oa1, 0, 0, 0);
;                 ob0 = __builtin_amdgcn_mfma_f32_32x32x16_bf16(v0, pfb, ob0, 0, 0, 0);
;                 ob1 = __builtin_amdgcn_mfma_f32_32x32x16_bf16(v1, pfb, ob1, 0, 0, 0);
;             }
.LBB0_392:
	v_exp_f32_e32 v112, v112
	v_exp_f32_e32 v113, v113
	v_exp_f32_e32 v114, v114
	v_exp_f32_e32 v115, v115
	v_exp_f32_e32 v116, v116
	v_add_f32_e32 v180, v113, v112
	v_exp_f32_e32 v117, v117
	v_add_f32_e32 v180, v114, v180
	v_exp_f32_e32 v118, v118
	v_add_f32_e32 v180, v115, v180
	v_exp_f32_e32 v119, v119
	v_add_f32_e32 v180, v116, v180
	v_exp_f32_e32 v120, v120
	v_add_f32_e32 v180, v117, v180
	v_exp_f32_e32 v121, v121
	v_add_f32_e32 v180, v118, v180
	v_exp_f32_e32 v122, v122
	v_add_f32_e32 v180, v119, v180
	v_exp_f32_e32 v123, v123
	v_add_f32_e32 v180, v120, v180
	v_exp_f32_e32 v124, v124
	v_add_f32_e32 v180, v121, v180
	v_exp_f32_e32 v125, v125
	v_add_f32_e32 v180, v122, v180
	v_exp_f32_e32 v126, v126
	v_add_f32_e32 v180, v123, v180
	v_exp_f32_e32 v127, v127
	v_add_f32_e32 v180, v124, v180
	v_exp_f32_e32 v182, v80
	v_add_f32_e32 v180, v125, v180
	v_exp_f32_e32 v210, v81
	v_add_f32_e32 v80, v126, v180
	v_exp_f32_e32 v211, v82
	v_add_f32_e32 v80, v127, v80
	v_exp_f32_e32 v212, v83
	v_add_f32_e32 v80, v182, v80
	v_exp_f32_e32 v213, v84
	v_add_f32_e32 v80, v210, v80
	v_exp_f32_e32 v214, v85
	v_add_f32_e32 v80, v211, v80
	v_exp_f32_e32 v215, v86
	v_add_f32_e32 v80, v212, v80
	v_exp_f32_e32 v216, v87
	v_add_f32_e32 v80, v213, v80
	v_exp_f32_e32 v217, v88
	v_add_f32_e32 v80, v214, v80
	v_exp_f32_e32 v219, v89
	v_add_f32_e32 v80, v215, v80
	v_add_f32_e32 v80, v216, v80
	v_add_f32_e32 v80, v217, v80
	v_add_f32_e32 v223, v219, v80
	v_exp_f32_e32 v224, v90
	v_exp_f32_e32 v225, v91
	v_exp_f32_e32 v92, v92
	v_add_u32_e32 v80, s10, v177
	v_sub_f32_e32 v81, v96, v185
	v_add_u32_e32 v88, v80, v164
	v_exp_f32_e32 v183, v81
	v_sub_f32_e32 v81, v97, v185
	v_add_u32_e32 v180, 0x4800, v88
	v_add_u32_e32 v181, 0x6800, v88
	v_exp_f32_e32 v188, v81
	ds_read2_b64 v[80:83], v180 offset1:2
	ds_read2_b64 v[88:91], v181 offset0:32 offset1:34
	v_sub_f32_e32 v96, v99, v185
	v_sub_f32_e32 v84, v98, v185
	v_exp_f32_e32 v190, v96
	v_sub_f32_e32 v96, v100, v185
	v_exp_f32_e32 v189, v84
	v_cvt_pk_bf16_f32 v84, v112, v113
	v_cvt_pk_bf16_f32 v85, v114, v115
	v_cvt_pk_bf16_f32 v86, v116, v117
	v_cvt_pk_bf16_f32 v87, v118, v119
	v_exp_f32_e32 v191, v96
	v_sub_f32_e32 v96, v101, v185
	s_waitcnt lgkmcnt(1)
	v_mfma_f32_32x32x16_bf16 v[48:63], v[80:83], v[84:87], v[48:63]
	v_exp_f32_e32 v192, v96
	v_sub_f32_e32 v96, v102, v185
	v_exp_f32_e32 v193, v96
	v_sub_f32_e32 v96, v107, v185
	v_exp_f32_e32 v198, v96
	v_sub_f32_e32 v96, v108, v185
	v_exp_f32_e32 v199, v96
	s_waitcnt lgkmcnt(0)
	v_mfma_f32_32x32x16_bf16 v[32:47], v[88:91], v[84:87], v[32:47]
	v_sub_f32_e32 v84, v103, v185
	v_exp_f32_e32 v194, v84
	v_cvt_pk_bf16_f32 v84, v183, v188
	v_cvt_pk_bf16_f32 v85, v189, v190
	v_cvt_pk_bf16_f32 v86, v191, v192
	v_cvt_pk_bf16_f32 v87, v193, v194
	v_sub_f32_e32 v96, v109, v185
	v_exp_f32_e32 v204, v96
	v_mfma_f32_32x32x16_bf16 v[16:31], v[80:83], v[84:87], v[16:31]
	v_exp_f32_e32 v93, v93
	v_sub_f32_e32 v80, v104, v185
	v_exp_f32_e32 v195, v80
	v_sub_f32_e32 v80, v105, v185
	v_exp_f32_e32 v196, v80
	ds_read2_b64 v[80:83], v180 offset0:4 offset1:6
	v_mfma_f32_32x32x16_bf16 v[0:15], v[88:91], v[84:87], v[0:15]
	ds_read2_b64 v[88:91], v181 offset0:36 offset1:38
	v_sub_f32_e32 v84, v106, v185
	v_exp_f32_e32 v197, v84
	v_cvt_pk_bf16_f32 v84, v120, v121
	v_cvt_pk_bf16_f32 v85, v122, v123
	v_cvt_pk_bf16_f32 v86, v124, v125
	v_cvt_pk_bf16_f32 v87, v126, v127
	v_sub_f32_e32 v96, v110, v185
	v_exp_f32_e32 v205, v96
	s_waitcnt lgkmcnt(1)
	v_mfma_f32_32x32x16_bf16 v[48:63], v[80:83], v[84:87], v[48:63]
	v_sub_f32_e32 v64, v64, v185
	v_exp_f32_e32 v207, v64
	v_sub_f32_e32 v64, v65, v185
	v_exp_f32_e32 v208, v64
	v_sub_f32_e32 v64, v66, v185
	v_exp_f32_e32 v209, v64
	v_sub_f32_e32 v64, v67, v185
	s_waitcnt lgkmcnt(0)
	v_mfma_f32_32x32x16_bf16 v[32:47], v[88:91], v[84:87], v[32:47]
	v_sub_f32_e32 v84, v111, v185
	v_exp_f32_e32 v206, v84
	v_cvt_pk_bf16_f32 v84, v195, v196
	v_cvt_pk_bf16_f32 v85, v197, v198
	v_cvt_pk_bf16_f32 v86, v199, v204
	v_cvt_pk_bf16_f32 v87, v205, v206
	s_nop 1
	s_nop 1
	v_mfma_f32_32x32x16_bf16 v[16:31], v[80:83], v[84:87], v[16:31]
	v_exp_f32_e32 v94, v94
	ds_read2_b64 v[80:83], v180 offset0:8 offset1:10
	v_mfma_f32_32x32x16_bf16 v[0:15], v[88:91], v[84:87], v[0:15]
	ds_read2_b64 v[88:91], v181 offset0:40 offset1:42
	v_cvt_pk_bf16_f32 v84, v182, v210
	v_exp_f32_e32 v210, v64
	v_sub_f32_e32 v64, v68, v185
	v_cvt_pk_bf16_f32 v85, v211, v212
	v_exp_f32_e32 v211, v64
	v_sub_f32_e32 v64, v69, v185
	v_exp_f32_e32 v212, v64
	v_sub_f32_e32 v64, v70, v185
	v_cvt_pk_bf16_f32 v86, v213, v214
	v_exp_f32_e32 v213, v64
	v_sub_f32_e32 v64, v71, v185
	v_exp_f32_e32 v214, v64
	v_cvt_pk_bf16_f32 v87, v215, v216
	v_cvt_pk_bf16_f32 v64, v207, v208
	s_waitcnt lgkmcnt(1)
	v_mfma_f32_32x32x16_bf16 v[48:63], v[80:83], v[84:87], v[48:63]
	v_cvt_pk_bf16_f32 v65, v209, v210
	v_cvt_pk_bf16_f32 v66, v211, v212
	v_cvt_pk_bf16_f32 v67, v213, v214
	s_waitcnt lgkmcnt(0)
	v_mfma_f32_32x32x16_bf16 v[32:47], v[88:91], v[84:87], v[32:47]
	v_exp_f32_e32 v84, v95
	v_sub_f32_e32 v68, v72, v185
	v_exp_f32_e32 v215, v68
	v_sub_f32_e32 v68, v73, v185
	v_exp_f32_e32 v216, v68
	ds_read2_b64 v[68:71], v180 offset0:12 offset1:14
	v_sub_f32_e32 v72, v75, v185
	v_mfma_f32_32x32x16_bf16 v[16:31], v[80:83], v[64:67], v[16:31]
	ds_read2_b64 v[80:83], v181 offset0:44 offset1:46
	v_exp_f32_e32 v221, v72
	v_sub_f32_e32 v72, v76, v185
	v_exp_f32_e32 v222, v72
	v_sub_f32_e32 v72, v77, v185
	v_mfma_f32_32x32x16_bf16 v[0:15], v[88:91], v[64:67], v[0:15]
	v_sub_f32_e32 v64, v74, v185
	v_exp_f32_e32 v218, v64
	v_cvt_pk_bf16_f32 v64, v217, v219
	v_cvt_pk_bf16_f32 v65, v224, v225
	v_cvt_pk_bf16_f32 v66, v92, v93
	v_cvt_pk_bf16_f32 v67, v94, v84
	v_exp_f32_e32 v217, v72
	v_sub_f32_e32 v72, v78, v185
	s_waitcnt lgkmcnt(1)
; #define LAS __attribute__((address_space(3)))
; template <int DK, bool IS_A>
; __device__ __forceinline__ void attn_unit(const Params& P, int l, LAS unsigned char* lds, int b, int grp, int qtok0, int nkeys) {
;     ...
;             __builtin_amdgcn_s_setprio(1);
; #pragma unroll
;             for (int i = 0; i < DK / 16; ++i)
; #pragma unroll
;                 for (int jj = 0; jj < 2; ++jj) {
;                     const bf16x8 kf = *(const LAS bf16x8*)(kb + jj * 32 * AK_PITCH + i * 32);
;                     pa[jj] = __builtin_amdgcn_mfma_f32_32x32x16_bf16(kf, qa[i], pa[jj], 0, 0, 0);
;                     pb[jj] = __builtin_amdgcn_mfma_f32_32x32x16_bf16(kf, qb[i], pb[jj], 0, 0, 0);
;                 }
;             __builtin_amdgcn_s_setprio(0);
;     ...
;             AT_SOFTMAX(pa, ma, la, oa0, oa1);
;             AT_SOFTMAX(pb, mb, lb_, ob0, ob1);
;     ...
; #pragma unroll
;             for (int ks = 0; ks < 4; ++ks) {
;                 const int o8 = 8 * (ks & 1);
;                 u32x4 w; const f32x16& xa = pa[ks >> 1]; const f32x16& xb = pb[ks >> 1];
;                 w.x = pk2(xa[o8], xa[o8 + 1]); w.y = pk2(xa[o8 + 2], xa[o8 + 3]); w.z = pk2(xa[o8 + 4], xa[o8 + 5]); w.w = pk2(xa[o8 + 6], xa[o8 + 7]);
;                 const bf16x8 pfa = __builtin_bit_cast(bf16x8, w);
;                 w.x = pk2(xb[o8], xb[o8 + 1]); w.y = pk2(xb[o8 + 2], xb[o8 + 3]); w.z = pk2(xb[o8 + 4], xb[o8 + 5]); w.w = pk2(xb[o8 + 6], xb[o8 + 7]);
;                 const bf16x8 pfb = __builtin_bit_cast(bf16x8, w);
;                 const u32x2 a0 = *(const LAS u32x2*)(vb + ks * 32), a1 = *(const LAS u32x2*)(vb + ks * 32 + 16);
;                 const u32x2 c0 = *(const LAS u32x2*)(vb + 32 * AV_PITCH + ks * 32), c1 = *(const LAS u32x2*)(vb + 32 * AV_PITCH + ks * 32 + 16);
;                 const bf16x8 v0 = __builtin_bit_cast(bf16x8, ((u32x4){a0.x, a0.y, a1.x, a1.y})), v1 = __builtin_bit_cast(bf16x8, ((u32x4){c0.x, c0.y, c1.x, c1.y}));
;                 oa0 = __builtin_amdgcn_mfma_f32_32x32x16_bf16(v0, pfa, oa0, 0, 0, 0);
;                 oa1 = __builtin_amdgcn_mfma_f32_32x32x16_bf16(v1, pfa, oa1, 0, 0, 0);
;                 ob0 = __builtin_amdgcn_mfma_f32_32x32x16_bf16(v0, pfb, ob0, 0, 0, 0);
;                 ob1 = __builtin_amdgcn_mfma_f32_32x32x16_bf16(v1, pfb, ob1, 0, 0, 0);
;             }
	v_mfma_f32_32x32x16_bf16 v[48:63], v[68:71], v[64:67], v[48:63]
	v_exp_f32_e32 v219, v72
	s_waitcnt lgkmcnt(0)
	v_mfma_f32_32x32x16_bf16 v[32:47], v[80:83], v[64:67], v[32:47]
	v_sub_f32_e32 v64, v79, v185
	v_exp_f32_e32 v220, v64
	v_cvt_pk_bf16_f32 v64, v215, v216
	v_cvt_pk_bf16_f32 v65, v218, v221
	v_cvt_pk_bf16_f32 v66, v222, v217
	v_cvt_pk_bf16_f32 v67, v219, v220
	s_nop 1
	s_nop 1
	v_mfma_f32_32x32x16_bf16 v[16:31], v[68:71], v[64:67], v[16:31]
	v_add_f32_e32 v68, v224, v223
	v_add_f32_e32 v68, v225, v68
	v_add_f32_e32 v68, v92, v68
	v_add_f32_e32 v68, v93, v68
	v_add_f32_e32 v68, v94, v68
	v_add_f32_e32 v68, v84, v68
	v_add_f32_e32 v184, v184, v68
	v_mfma_f32_32x32x16_bf16 v[0:15], v[80:83], v[64:67], v[0:15]
	s_setprio 1
	ds_read_b128 v[64:67], v186 offset:9216
	ds_read_b128 v[224:227], v186 offset:9248
	s_waitcnt lgkmcnt(1)
	v_mfma_f32_32x32x16_bf16 v[112:127], v[64:67], v[142:145], v[236:251]
	v_mfma_f32_32x32x16_bf16 v[96:111], v[64:67], v[158:161], 0
	ds_read_b128 v[64:67], v186 offset:13824
	s_waitcnt lgkmcnt(1)
	v_mfma_f32_32x32x16_bf16 v[112:127], v[224:227], v[150:153], v[112:127]
	v_mfma_f32_32x32x16_bf16 v[96:111], v[224:227], v[154:157], v[96:111]
	ds_read_b128 v[224:227], v186 offset:13856
	s_waitcnt lgkmcnt(1)
	v_mfma_f32_32x32x16_bf16 v[80:95], v[64:67], v[142:145], v[236:251]
	v_mfma_f32_32x32x16_bf16 v[64:79], v[64:67], v[158:161], 0
	s_waitcnt lgkmcnt(0)
	v_mfma_f32_32x32x16_bf16 v[80:95], v[224:227], v[150:153], v[80:95]
	v_mfma_f32_32x32x16_bf16 v[64:79], v[224:227], v[154:157], v[64:79]
	s_setprio 0
	s_nop 9
	v_max_f32_e32 v182, v112, v80
	v_max3_f32 v186, v81, v114, v82
	v_max3_f32 v182, v182, v113, v115
	v_max3_f32 v186, v186, v116, v84
	v_max3_f32 v182, v182, v83, v117
	v_max3_f32 v186, v186, v118, v86
	v_max3_f32 v182, v182, v85, v119
	v_max3_f32 v186, v186, v120, v88
	v_max3_f32 v182, v182, v87, v121
	v_max3_f32 v186, v186, v122, v90
	v_max3_f32 v182, v182, v89, v123
	v_max3_f32 v186, v186, v124, v92
	v_max3_f32 v182, v182, v91, v125
	v_max3_f32 v186, v186, v126, v94
	v_max3_f32 v182, v182, v93, v127
	v_max3_f32 v182, v182, v95, v186
	v_sub_f32_e32 v182, v182, v236
	ds_bpermute_b32 v186, v163, v182
	s_waitcnt lgkmcnt(0)
	v_max3_f32 v182, v187, v182, v186
	v_add_f32_e32 v186, 0x41000000, v187
	v_cmp_gt_f32_e32 vcc, v182, v186
	s_cbranch_vccz .LBB0_394
	v_add_f32_e32 v186, v182, v236
	v_sub_f32_e32 v112, v112, v186
	v_sub_f32_e32 v113, v113, v186
	v_sub_f32_e32 v114, v114, v186
	v_sub_f32_e32 v115, v115, v186
	v_sub_f32_e32 v116, v116, v186
	v_sub_f32_e32 v117, v117, v186
	v_sub_f32_e32 v118, v118, v186
	v_sub_f32_e32 v119, v119, v186
	v_sub_f32_e32 v120, v120, v186
	v_sub_f32_e32 v121, v121, v186
	v_sub_f32_e32 v122, v122, v186
	v_sub_f32_e32 v123, v123, v186
	v_sub_f32_e32 v124, v124, v186
	v_sub_f32_e32 v125, v125, v186
	v_sub_f32_e32 v126, v126, v186
	v_sub_f32_e32 v127, v127, v186
	v_sub_f32_e32 v80, v80, v186
	v_sub_f32_e32 v81, v81, v186
	v_sub_f32_e32 v82, v82, v186
	v_sub_f32_e32 v83, v83, v186
	v_sub_f32_e32 v84, v84, v186
	v_sub_f32_e32 v85, v85, v186
	v_sub_f32_e32 v86, v86, v186
	v_sub_f32_e32 v87, v87, v186
	v_sub_f32_e32 v88, v88, v186
	v_sub_f32_e32 v89, v89, v186
	v_sub_f32_e32 v90, v90, v186
	v_sub_f32_e32 v91, v91, v186
	v_sub_f32_e32 v92, v92, v186
	v_sub_f32_e32 v93, v93, v186
	v_sub_f32_e32 v94, v94, v186
	v_sub_f32_e32 v95, v95, v186
	v_sub_f32_e32 v236, 0, v182
	v_sub_f32_e32 v237, 0, v182
	v_sub_f32_e32 v238, 0, v182
	v_sub_f32_e32 v239, 0, v182
	v_sub_f32_e32 v240, 0, v182
	v_sub_f32_e32 v241, 0, v182
	v_sub_f32_e32 v242, 0, v182
	v_sub_f32_e32 v243, 0, v182
	v_sub_f32_e32 v244, 0, v182
	v_sub_f32_e32 v245, 0, v182
	v_sub_f32_e32 v246, 0, v182
	v_sub_f32_e32 v247, 0, v182
	v_sub_f32_e32 v248, 0, v182
	v_sub_f32_e32 v249, 0, v182
	v_sub_f32_e32 v250, 0, v182
	v_sub_f32_e32 v251, 0, v182
	v_sub_f32_e32 v186, v187, v182
	v_exp_f32_e32 v186, v186
	s_nop 0
	v_pk_mul_f32 v[62:63], v[62:63], v[186:187] op_sel_hi:[1,0]
	v_pk_mul_f32 v[60:61], v[60:61], v[186:187] op_sel_hi:[1,0]
	v_pk_mul_f32 v[58:59], v[58:59], v[186:187] op_sel_hi:[1,0]
	v_pk_mul_f32 v[56:57], v[56:57], v[186:187] op_sel_hi:[1,0]
	v_pk_mul_f32 v[54:55], v[54:55], v[186:187] op_sel_hi:[1,0]
	v_pk_mul_f32 v[52:53], v[52:53], v[186:187] op_sel_hi:[1,0]
	v_pk_mul_f32 v[50:51], v[50:51], v[186:187] op_sel_hi:[1,0]
	v_pk_mul_f32 v[48:49], v[48:49], v[186:187] op_sel_hi:[1,0]
	v_pk_mul_f32 v[46:47], v[46:47], v[186:187] op_sel_hi:[1,0]
	v_pk_mul_f32 v[44:45], v[44:45], v[186:187] op_sel_hi:[1,0]
	v_pk_mul_f32 v[42:43], v[42:43], v[186:187] op_sel_hi:[1,0]
	v_pk_mul_f32 v[40:41], v[40:41], v[186:187] op_sel_hi:[1,0]
	v_pk_mul_f32 v[38:39], v[38:39], v[186:187] op_sel_hi:[1,0]
	v_pk_mul_f32 v[36:37], v[36:37], v[186:187] op_sel_hi:[1,0]
	v_pk_mul_f32 v[34:35], v[34:35], v[186:187] op_sel_hi:[1,0]
	v_pk_mul_f32 v[32:33], v[32:33], v[186:187] op_sel_hi:[1,0]
	v_mul_f32_e32 v184, v184, v186
	s_branch .LBB0_395
